# pipelined attention v2: V reads hoisted to the start of the softmax block, next-tile staging ds_writes moved inside the MFMA block
# baseline (speedup 1.0000x reference)
; DI int opaque_tid() { int t = threadIdx.x; asm volatile("" : "+v"(t)); return t; }
; DI void attn_item(const Params& p, unsigned char* lds, int b, int hd, int qb, float lam) {
;     const int tid = opaque_tid(), lane = tid & 63, wave = tid >> 6, l31 = lane & 31, h = lane >> 5;
;     const int sub = wave >> 2, rt = wave & 3;
;     const bf16_t* aq = (const bf16_t*)((unsigned char*)p.out + DO_AQ);
;     const bf16_t* ak = (const bf16_t*)(p.ws + OFF_AK);
;     const bf16_t* avT = (const bf16_t*)(p.ws + OFF_AVT);
;     const bf16_t* akm = (const bf16_t*)(p.ws + OFF_AKM);
;     const bf16_t* avTm = (const bf16_t*)(p.ws + OFF_AVTM);
;     bf16_t* az = (bf16_t*)(p.ws + OFF_AZ);
;     const int qs = qb * 128 + rt * 32 + l31;
;     const size_t grow = (size_t)b * 4096 + qs;
;     bf16x8 qf[4];
; #pragma unroll
;     for (int ks = 0; ks < 4; ++ks) qf[ks] = *(const bf16x8*)(aq + grow * 1024 + hd * 128 + sub * 64 + ks * 16 + 8 * h);
;     f32x16 O[4];
; #pragma unroll
;     for (int d = 0; d < 4; ++d)
; #pragma unroll
;         for (int i = 0; i < 16; ++i) O[d][i] = 0.f;
;     float m = 0.f, l = 0.f;
;     const int T = 2 * qb + 3;
;     u32x4 k0r[2], v0r[2];
;     const int krow_ = tid >> 4, kc_ = tid & 15, vdv_ = tid >> 3, vc_ = tid & 7;
;     const bf16_t* kp = ak + ((size_t)b * 4096 + krow_) * 1024 + hd * 128 + kc_ * 8;
;     const bf16_t* vp_ = avT + ((size_t)(b * 8 + hd) * 128 + vdv_) * 4096 + vc_ * 8;
;     ...
;     {
;         const bf16_t* km_ = akm + (size_t)krow_ * 1024 + hd * 128 + kc_ * 8;
;         k0r[0] = *(const u32x4*)km_; k0r[1] = *(const u32x4*)(km_ + 32 * 1024);
;         const bf16_t* vm_ = avTm + (size_t)(hd * 128 + vdv_) * 64 + vc_ * 8;
;         v0r[0] = *(const u32x4*)vm_; v0r[1] = *(const u32x4*)(vm_ + 64 * 64);
;     }
;     u32x4 k1r[2], v1r[2];
;     A_LOAD_REAL(k1r, v1r);
; #pragma unroll
;     for (int ks = 0; ks < 4; ++ks) asm volatile("" : "+v"(qf[ks]));
;     A_STORE(k0r, v0r, 0);
;     __syncthreads();
.LBB0_1809:
	s_or_b64 exec, exec, s[4:5]
	s_add_i32 s0, 0, 0x25000
	s_cmp_lg_u32 s0, -1
	s_cselect_b32 s0, s0, 0
	s_cselect_b32 s4, s57, 0
	s_waitcnt vmcnt(0)
	v_mov_b32_e32 v2, s0
	v_mov_b32_e32 v3, s4
	s_waitcnt lgkmcnt(0)
	s_barrier
	flat_load_dword v1, v[2:3] sc0 sc1
	s_waitcnt vmcnt(0) lgkmcnt(0)
	s_barrier
	v_readfirstlane_b32 s8, v1
	s_cmp_eq_u32 s8, -1
	s_cbranch_scc1 .LBB0_1823
	s_lshr_b32 s9, s8, 16
	s_and_b32 s0, s8, 0xffff
	s_cmp_gt_u32 s0, 7
	s_mov_b64 s[4:5], -1
	s_cbranch_scc0 .LBB0_1831
	s_add_i32 s4, s0, -8
	s_lshr_b32 s0, s4, 2
	s_and_b32 s0, s0, 0x3ffffffc
	s_and_b32 s5, s8, 3
	s_or_b32 s0, s0, s5
	v_mov_b32_e32 v132, v186
	s_sub_i32 s0, 31, s0
	s_lshl_b32 s6, s0, 7
	v_lshrrev_b32_e32 v1, 1, v132
	v_and_b32_e32 v146, 31, v132
	v_and_b32_e32 v148, 0x60, v1
	s_bfe_u32 s11, s4, 0x20002
	v_or3_b32 v138, v148, s6, v146
	s_lshl_b32 s54, s11, 12
	v_ashrrev_i32_e32 v139, 31, v138
	v_lshl_add_u64 v[2:3], v[138:139], 0, s[54:55]
	v_ashrrev_i32_e32 v147, 8, v132
	v_lshlrev_b64 v[136:137], 11, v[2:3]
	v_lshl_add_u64 v[2:3], s[68:69], 0, v[136:137]
	s_lshl_b32 s6, s9, 8
	s_mov_b32 s7, s55
	v_lshlrev_b32_e32 v4, 6, v147
	v_lshl_add_u64 v[2:3], v[2:3], 0, s[6:7]
	v_ashrrev_i32_e32 v5, 31, v4
	v_lshl_add_u64 v[2:3], v[4:5], 1, v[2:3]
	v_ashrrev_i32_e32 v4, 4, v132
	v_ashrrev_i32_e32 v5, 31, v4
	v_lshlrev_b64 v[12:13], 11, v[4:5]
	v_bfe_u32 v149, v132, 5, 1
	v_lshlrev_b32_e32 v1, 4, v132
	v_lshl_add_u64 v[12:13], s[64:65], 0, v[12:13]
	v_lshlrev_b32_e32 v98, 4, v149
	v_and_b32_e32 v140, 0xf0, v1
	v_mov_b32_e32 v141, v99
	v_lshl_add_u64 v[12:13], v[12:13], 0, s[6:7]
	v_lshl_add_u64 v[2:3], v[2:3], 0, v[98:99]
	v_lshl_add_u64 v[12:13], v[12:13], 0, v[140:141]
	global_load_dwordx4 v[100:103], v[2:3], off
	global_load_dwordx4 v[104:107], v[2:3], off offset:32
	global_load_dwordx4 v[108:111], v[2:3], off offset:64
	global_load_dwordx4 v[112:115], v[2:3], off offset:96
	global_load_dwordx4 v[116:119], v[12:13], off
	v_add_co_u32_e32 v2, vcc, s43, v12
	s_lshl_b32 s10, s9, 7
	v_ashrrev_i32_e32 v6, 3, v132
	v_addc_co_u32_e32 v3, vcc, 0, v13, vcc
	global_load_dwordx4 v[120:123], v[2:3], off
	v_add_u32_e32 v2, s10, v6
	v_ashrrev_i32_e32 v3, 31, v2
	v_lshlrev_b64 v[2:3], 7, v[2:3]
	v_and_b32_e32 v10, 0x70, v1
	v_mov_b32_e32 v11, v99
	v_lshl_add_u64 v[2:3], s[62:63], 0, v[2:3]
	v_lshl_add_u64 v[2:3], v[2:3], 0, v[10:11]
	global_load_dwordx4 v[124:127], v[2:3], off
	v_lshl_add_u64 v[8:9], v[4:5], 0, s[54:55]
	v_lshlrev_b64 v[8:9], 11, v[8:9]
	v_add_co_u32_e32 v2, vcc, s56, v2
	v_lshl_add_u64 v[8:9], s[44:45], 0, v[8:9]
	s_lshl_b32 s11, s11, 10
	v_addc_co_u32_e32 v3, vcc, 0, v3, vcc
	v_lshl_add_u64 v[8:9], v[8:9], 0, s[6:7]
	s_add_i32 s54, s11, s10
	v_ashrrev_i32_e32 v7, 31, v6
	global_load_dwordx4 v[128:131], v[2:3], off
	v_lshl_add_u64 v[82:83], v[8:9], 0, v[140:141]
	v_lshl_add_u64 v[8:9], v[6:7], 0, s[54:55]
	v_lshlrev_b64 v[8:9], 13, v[8:9]
	v_lshl_add_u64 v[8:9], s[60:61], 0, v[8:9]
	v_add_co_u32_e32 v2, vcc, s43, v82
	v_lshl_add_u64 v[84:85], v[8:9], 0, v[10:11]
	s_nop 0
	v_addc_co_u32_e32 v3, vcc, 0, v83, vcc
	v_add_co_u32_e32 v8, vcc, s74, v84
	global_load_dwordx4 v[74:77], v[82:83], off
	global_load_dwordx4 v[70:73], v[84:85], off
	v_addc_co_u32_e32 v9, vcc, 0, v85, vcc
	global_load_dwordx4 v[78:81], v[2:3], off
	global_load_dwordx4 v[66:69], v[8:9], off
	v_lshlrev_b32_e32 v2, 3, v132
	v_mul_lo_u32 v139, v4, s75
	v_add_u32_e32 v4, 0x200, v132
	v_and_b32_e32 v150, 0x60, v1
	v_and_b32_e32 v151, 8, v2
	v_lshrrev_b32_e32 v5, 4, v4
	v_add3_u32 v1, 0, v150, v151
	v_mul_lo_u32 v152, v6, s52
	v_add_u32_e32 v3, 0, v140
	v_mul_lo_u32 v141, v5, s75
	v_add_u32_e32 v97, v1, v152
	v_add_u32_e32 v87, v3, v139
	v_add_u32_e32 v96, v3, v141
	v_add_u32_e32 v2, 0x4000, v97
	s_waitcnt vmcnt(11)
	s_waitcnt vmcnt(10)
	s_waitcnt vmcnt(9)
	s_waitcnt vmcnt(8)
	s_waitcnt vmcnt(7)
	ds_write_b128 v87, v[116:119]
	v_mad_u32_u24 v42, v146, s75, 0
	v_lshl_or_b32 v154, v147, 7, v98
	s_waitcnt vmcnt(6)
	ds_write_b128 v96, v[120:123]
	s_waitcnt vmcnt(5)
	ds_write2_b64 v2, v[124:125], v[126:127] offset0:128 offset1:130
	v_lshrrev_b32_e32 v2, 3, v4
	v_mul_lo_u32 v153, v2, s52
	v_add_u32_e32 v155, v1, v153
	v_add_u32_e32 v1, 0x4000, v155
	s_waitcnt vmcnt(4)
	ds_write2_b64 v1, v[128:129], v[130:131] offset0:128 offset1:130
	v_add_u32_e32 v1, v42, v154
	s_waitcnt lgkmcnt(0)
	s_barrier
; DI void attn_s(const unsigned char* sK, int tt, int qb, int qs, int sub, int l31, int h,
;                const bf16x8 (&qf)[4], f32x16 (&O)[4], float& m, float& l, bf16x8 (&pb)[4]) {
;     ...
;         for (int i = 0; i < 4; ++i) st[i & 1] = MFMA32(ka[i], qf[i >> 1], st[i & 1]);
;         __builtin_amdgcn_sched_barrier(0);
; #pragma unroll
;         for (int i = 0; i < 4; ++i) st[i & 1] = MFMA32(kc[i], qf[2 + (i >> 1)], st[i & 1]);
;     }
;     if (tt == 0) {
; #pragma unroll
;         for (int i = 0; i < 16; ++i) { st[0][i] = -INFINITY; if (i < 8) st[1][i] = -INFINITY; }
;     } else if (tt >= 2 * qb + 1) {
;         const int kbase = (tt - 1) * 64 + 4 * h;
; #pragma unroll
;         for (int k2 = 0; k2 < 2; ++k2)
; #pragma unroll
;             for (int i = 0; i < 16; ++i) {
;                 const int key = kbase + k2 * 32 + (i & 3) + 8 * (i >> 2);
;                 if (key > qs) st[k2][i] = -INFINITY;
;             }
;     }
;     float mx;
;     {
;         float t[11];
; #pragma unroll
;         for (int i = 0; i < 5; ++i) t[i] = max3f(st[0][3 * i], st[0][3 * i + 1], st[0][3 * i + 2]);
; #pragma unroll
;         for (int i = 0; i < 5; ++i) t[5 + i] = max3f(st[1][3 * i], st[1][3 * i + 1], st[1][3 * i + 2]);
;         t[10] = fmaxf(st[0][15], st[1][15]);
;         const float u0 = max3f(t[0], t[1], t[2]), u1 = max3f(t[3], t[4], t[5]), u2 = max3f(t[6], t[7], t[8]);
;         mx = max3f(max3f(u0, u1, u2), t[9], t[10]);
;     }
;     mx = xor32_max(mx);
;     if (tt == 0 || __builtin_amdgcn_ballot_w64(mx > 8.0f) != 0ull) {
;         const float delta = tt == 0 ? mx : fmaxf(mx, 0.f);
;         const float alpha = __builtin_amdgcn_exp2f(-delta);
;         m += delta;
;         l *= alpha;
; #pragma unroll
;         for (int d = 0; d < 4; ++d) O[d] = O[d] * alpha;
; #pragma unroll
;         for (int k2 = 0; k2 < 2; ++k2) st[k2] = st[k2] - delta;
;     }
; #pragma unroll
;     for (int k2 = 0; k2 < 2; ++k2)
; #pragma unroll
;         for (int i = 0; i < 16; ++i) st[k2][i] = __builtin_amdgcn_exp2f(st[k2][i]);
;     {
;         const f32x16 sv = st[0] + st[1];
;         const float ps = (((sv[0] + sv[1]) + (sv[2] + sv[3])) + ((sv[4] + sv[5]) + (sv[6] + sv[7]))) + (((sv[8] + sv[9]) + (sv[10] + sv[11])) + ((sv[12] + sv[13]) + (sv[14] + sv[15])));
;         l += ps;
;     }
; #pragma unroll
;     for (int k4 = 0; k4 < 4; ++k4) {
	ds_read_b128 v[26:29], v1 offset:8704
	ds_read_b128 v[30:33], v1 offset:8736
	ds_read_b128 v[34:37], v1 offset:8768
	ds_read_b128 v[38:41], v1 offset:8800
	v_mov_b32_e32 v10, v0
	v_mov_b32_e32 v11, v0
	v_mov_b32_e32 v12, v0
	v_mov_b32_e32 v13, v0
	v_mov_b32_e32 v14, v0
	v_mov_b32_e32 v15, v0
	v_mov_b32_e32 v1, v0
	v_mov_b32_e32 v2, v0
	v_mov_b32_e32 v3, v0
	v_mov_b32_e32 v4, v0
	v_mov_b32_e32 v5, v0
	v_mov_b32_e32 v6, v0
	v_mov_b32_e32 v7, v0
	v_mov_b32_e32 v8, v0
	v_mov_b32_e32 v9, v0
	v_mov_b64_e32 v[24:25], v[14:15]
	v_mov_b64_e32 v[22:23], v[12:13]
	v_mov_b64_e32 v[20:21], v[10:11]
	v_mov_b64_e32 v[18:19], v[8:9]
	v_mov_b64_e32 v[16:17], v[6:7]
	v_mov_b64_e32 v[14:15], v[4:5]
	v_mov_b64_e32 v[12:13], v[2:3]
	v_mov_b64_e32 v[10:11], v[0:1]
	s_waitcnt lgkmcnt(3)
	s_nop 0
	v_mfma_f32_32x32x16_bf16 v[10:25], v[26:29], v[100:103], v[10:25]
	s_waitcnt lgkmcnt(2)
	v_mfma_f32_32x32x16_bf16 v[10:25], v[30:33], v[104:107], v[10:25]
	s_waitcnt lgkmcnt(1)
	v_mfma_f32_32x32x16_bf16 v[10:25], v[34:37], v[108:111], v[10:25]
	v_max3_f32 v1, v188, v188, v188
	s_nop 0
	v_max3_f32 v2, v1, v1, v1
	s_waitcnt lgkmcnt(0)
	v_mfma_f32_32x32x16_bf16 v[10:25], v[38:41], v[112:115], v[10:25]
	v_max3_f32 v3, v188, v188, v18
	v_max3_f32 v4, v19, v20, v21
	v_max3_f32 v5, v22, v23, v24
	s_nop 0
	v_max3_f32 v1, v1, v3, v4
	s_nop 10
	v_max_f32_e32 v6, v25, v25
	v_max3_f32 v1, v2, v2, v1
	v_max_f32_e32 v6, 0xff800000, v6
	v_max3_f32 v1, v1, v5, v6
	s_nop 0
	v_mov_b32_e32 v2, v1
	s_nop 1
	v_permlane32_swap_b32_e32 v1, v2
	v_max_f32_e32 v2, v2, v2
	v_max_f32_e32 v1, v1, v1
	v_max_f32_e32 v86, v1, v2
	v_sub_f32_e32 v1, 0xff800000, v86
	v_sub_f32_e32 v19, v19, v86
	v_sub_f32_e32 v26, v18, v86
	v_sub_f32_e32 v21, v21, v86
	v_sub_f32_e32 v20, v20, v86
	v_exp_f32_e32 v18, v1
	v_exp_f32_e32 v26, v26
	v_exp_f32_e32 v27, v19
	v_sub_f32_e32 v23, v23, v86
	v_sub_f32_e32 v22, v22, v86
	v_exp_f32_e32 v28, v20
	v_exp_f32_e32 v29, v21
	v_sub_f32_e32 v25, v25, v86
	v_sub_f32_e32 v24, v24, v86
	v_exp_f32_e32 v30, v22
	v_exp_f32_e32 v31, v23
	v_exp_f32_e32 v32, v24
	v_exp_f32_e32 v33, v25
	v_pk_add_f32 v[34:35], v[18:19], v[26:27] op_sel_hi:[0,1]
	v_add_f32_e32 v36, v18, v18
	v_pk_add_f32 v[24:25], v[18:19], v[28:29] op_sel_hi:[0,1]
	v_mov_b32_e32 v37, v34
	v_mov_b32_e32 v34, v36
	v_pk_add_f32 v[22:23], v[18:19], v[30:31] op_sel_hi:[0,1]
	v_pk_add_f32 v[34:35], v[36:37], v[34:35]
	v_mov_b32_e32 v37, v24
	v_mov_b32_e32 v24, v36
	v_pk_add_f32 v[20:21], v[18:19], v[32:33] op_sel_hi:[0,1]
	v_pk_add_f32 v[24:25], v[36:37], v[24:25]
	v_mov_b32_e32 v37, v22
	v_mov_b32_e32 v22, v36
	v_pk_add_f32 v[22:23], v[36:37], v[22:23]
	v_mov_b32_e32 v37, v20
	v_mov_b32_e32 v20, v36
	v_pk_add_f32 v[20:21], v[36:37], v[20:21]
	v_cvt_pk_bf16_f32 v88, v18, v18
	v_lshlrev_b32_e32 v18, 7, v146
	v_pk_add_f32 v[24:25], v[34:35], v[24:25]
	v_pk_add_f32 v[20:21], v[22:23], v[20:21]
	v_sub_u32_e32 v18, v42, v18
	v_pk_add_f32 v[20:21], v[24:25], v[20:21]
	v_add_u32_e32 v185, v18, v98
	v_add_f32_e32 v1, v20, v21
	ds_read_b128 v[18:21], v185 offset:17408
	ds_read_b128 v[22:25], v185 offset:22016
	ds_read_b128 v[92:95], v185 offset:26624
	ds_read_b128 v[142:145], v185 offset:31232
	v_exp_f32_e64 v184, -v86
	v_mov_b32_e32 v89, v88
	v_mov_b32_e32 v90, v88
	v_mov_b32_e32 v91, v88
	v_mul_f32_e32 v2, 0, v184
	v_mov_b32_e32 v3, v2
	v_mov_b32_e32 v4, v2
	v_mov_b32_e32 v5, v2
	v_mov_b32_e32 v6, v2
	v_mov_b32_e32 v7, v2
	v_mov_b32_e32 v8, v2
	v_mov_b32_e32 v9, v2
	v_mov_b32_e32 v10, v2
	v_mov_b32_e32 v11, v2
	v_mov_b32_e32 v12, v2
	v_mov_b32_e32 v13, v2
	v_mov_b32_e32 v14, v2
	v_mov_b32_e32 v15, v2
	v_mov_b32_e32 v16, v2
	v_mov_b32_e32 v17, v2
	v_cvt_pk_bf16_f32 v156, v26, v27
	v_cvt_pk_bf16_f32 v157, v28, v29
	v_cvt_pk_bf16_f32 v158, v30, v31
	v_cvt_pk_bf16_f32 v159, v32, v33
	ds_read_b128 v[160:163], v185 offset:17440
	ds_read_b128 v[164:167], v185 offset:22048
	ds_read_b128 v[168:171], v185 offset:26656
	ds_read_b128 v[172:175], v185 offset:31264
	s_waitcnt lgkmcnt(7)
	v_mfma_f32_32x32x16_bf16 v[50:65], v[18:21], v[88:91], v[2:17]
	s_waitcnt lgkmcnt(6)
	v_mfma_f32_32x32x16_bf16 v[34:49], v[22:25], v[88:91], v[2:17]
	s_waitcnt lgkmcnt(5)
	v_mfma_f32_32x32x16_bf16 v[18:33], v[92:95], v[88:91], v[2:17]
	s_waitcnt lgkmcnt(4)
	v_mfma_f32_32x32x16_bf16 v[2:17], v[142:145], v[88:91], v[2:17]
	ds_read_b128 v[92:95], v185 offset:17472
	ds_read_b128 v[142:145], v185 offset:22080
	ds_read_b128 v[176:179], v185 offset:26688
	ds_read_b128 v[180:183], v185 offset:31296
	s_waitcnt lgkmcnt(7)
	v_mfma_f32_32x32x16_bf16 v[50:65], v[160:163], v[88:91], v[50:65]
	s_waitcnt lgkmcnt(6)
	v_mfma_f32_32x32x16_bf16 v[34:49], v[164:167], v[88:91], v[34:49]
	s_waitcnt lgkmcnt(5)
	v_mfma_f32_32x32x16_bf16 v[18:33], v[168:171], v[88:91], v[18:33]
	s_waitcnt lgkmcnt(4)
	v_mfma_f32_32x32x16_bf16 v[2:17], v[172:175], v[88:91], v[2:17]
	ds_read_b128 v[160:163], v185 offset:17504
	ds_read_b128 v[164:167], v185 offset:22112
	ds_read_b128 v[168:171], v185 offset:26720
	ds_read_b128 v[172:175], v185 offset:31328
	s_waitcnt lgkmcnt(7)
	v_mfma_f32_32x32x16_bf16 v[50:65], v[92:95], v[88:91], v[50:65]
	s_waitcnt lgkmcnt(6)
	v_mfma_f32_32x32x16_bf16 v[34:49], v[142:145], v[88:91], v[34:49]
	s_waitcnt lgkmcnt(5)
	v_mfma_f32_32x32x16_bf16 v[18:33], v[176:179], v[88:91], v[18:33]
	s_waitcnt lgkmcnt(4)
	v_mfma_f32_32x32x16_bf16 v[2:17], v[180:183], v[88:91], v[2:17]
	s_waitcnt lgkmcnt(3)
	v_mfma_f32_32x32x16_bf16 v[50:65], v[160:163], v[156:159], v[50:65]
	s_waitcnt vmcnt(3)
	ds_write_b128 v87, v[74:77] offset:35840
	s_waitcnt vmcnt(1)
	ds_write_b128 v96, v[78:81] offset:35840
	v_add_u32_e32 v74, 0xd000, v97
	ds_write2_b64 v74, v[70:71], v[72:73] offset1:2
	v_add_u32_e32 v70, 0xd000, v155
	v_fmac_f32_e32 v1, 0, v184
	s_cmpk_gt_u32 s4, 0x7f
	s_waitcnt vmcnt(0)
	ds_write2_b64 v70, v[66:67], v[68:69] offset1:2
	s_waitcnt lgkmcnt(6)
	v_mfma_f32_32x32x16_bf16 v[34:49], v[164:167], v[156:159], v[34:49]
	s_waitcnt lgkmcnt(0)
	s_barrier
	v_mfma_f32_32x32x16_bf16 v[18:33], v[168:171], v[156:159], v[18:33]
	v_mfma_f32_32x32x16_bf16 v[2:17], v[172:175], v[156:159], v[2:17]
	s_cbranch_scc1 .LBB0_1824
	s_lshr_b32 s4, s4, 1
	s_lshl_b32 s5, s5, 1
	s_and_b32 s4, s4, 0x7ffffff8
	s_lshl_b32 s0, s0, 1
	s_or_b32 s4, s5, s4
	v_mul_u32_u24_e32 v155, 0x110, v146
	v_mul_u32_u24_e32 v156, 0x90, v146
	s_mov_b32 s13, 1
	s_add_i32 s6, s0, 3
	v_lshl_add_u64 v[142:143], v[84:85], 0, s[88:89]
	v_lshl_add_u64 v[142:143], v[142:143], 0, s[88:89]
	v_add_f32_e32 v157, 0, v86
	v_lshl_add_u64 v[144:145], v[82:83], 0, s[90:91]
	v_lshl_add_u64 v[144:145], v[144:145], 0, s[90:91]
	s_mov_b32 s7, 2
	v_lshl_or_b32 v158, v149, 2, 59
	s_sub_i32 s11, 0, s4
	s_movk_i32 s12, 0xffc0
	v_readfirstlane_b32 s99, v147
	s_cmp_eq_u32 s99, 1
	s_cbranch_scc0 .Lpipe_nooffs
	s_barrier
; #define MFMA32(a, b, c) __builtin_amdgcn_mfma_f32_32x32x16_bf16((a), (b), (c), 0, 0, 0)
; DI void attn_s(const unsigned char* sK, int tt, int qb, int qs, int sub, int l31, int h,
;                const bf16x8 (&qf)[4], f32x16 (&O)[4], float& m, float& l, bf16x8 (&pb)[4]) {
;     ...
;     for (int k2 = 0; k2 < 2; ++k2)
; #pragma unroll
;         for (int i = 0; i < 16; ++i) st[k2][i] = -m;
;     {
;         const unsigned char* kb = sK + l31 * A_KROWB + (sub * 64 + 8 * h) * 2;
;         bf16x8 ka[4], kc[4];
; #pragma unroll
;         for (int i = 0; i < 4; ++i) ka[i] = *(const bf16x8*)(kb + (i & 1) * 32 * A_KROWB + (i >> 1) * 32);
;         __builtin_amdgcn_sched_barrier(0);
; #pragma unroll
;         for (int i = 0; i < 4; ++i) kc[i] = *(const bf16x8*)(kb + (i & 1) * 32 * A_KROWB + (2 + (i >> 1)) * 32);
;         __builtin_amdgcn_sched_barrier(0);
; #pragma unroll
;         for (int i = 0; i < 4; ++i) st[i & 1] = MFMA32(ka[i], qf[i >> 1], st[i & 1]);
;         __builtin_amdgcn_sched_barrier(0);
; #pragma unroll
;         for (int i = 0; i < 4; ++i) st[i & 1] = MFMA32(kc[i], qf[2 + (i >> 1)], st[i & 1]);
.Lpipe_nooffs:
	s_barrier
	v_lshl_add_u64 v[184:185], v[82:83], 0, s[90:91]
	global_load_dwordx4 v[116:119], v[184:185], off
	s_nop 0
	v_lshl_add_u64 v[184:185], v[184:185], 0, s[92:93]
	global_load_dwordx4 v[120:123], v[184:185], off
	s_nop 0
	v_lshl_add_u64 v[184:185], v[84:85], 0, s[88:89]
	global_load_dwordx4 v[124:127], v[184:185], off
	s_nop 0
	v_add_co_u32_e32 v184, vcc, 0x80000, v184
	s_nop 1
	v_addc_co_u32_e32 v185, vcc, 0, v185, vcc
	global_load_dwordx4 v[128:131], v[184:185], off
	s_mul_i32 s98, s13, 0x8c00
	s_add_i32 s98, s98, 0
	v_add3_u32 v67, s98, v155, v154
	ds_read_b128 v[160:163], v67
	ds_read_b128 v[164:167], v67 offset:32
	ds_read_b128 v[168:171], v67 offset:8704
	ds_read_b128 v[172:175], v67 offset:8736
	v_xor_b32_e32 v66, 0x80000000, v157
	ds_read_b128 v[176:179], v67 offset:64
	ds_read_b128 v[180:183], v67 offset:96
	ds_read_b128 v[192:195], v67 offset:8768
	ds_read_b128 v[196:199], v67 offset:8800
	v_mov_b32_e32 v67, v66
	v_mov_b32_e32 v68, v66
	v_mov_b32_e32 v69, v66
	v_mov_b32_e32 v70, v66
	v_mov_b32_e32 v71, v66
	v_mov_b32_e32 v72, v66
	v_mov_b32_e32 v73, v66
	v_mov_b32_e32 v74, v66
	v_mov_b32_e32 v75, v66
	v_mov_b32_e32 v76, v66
	v_mov_b32_e32 v77, v66
	v_mov_b32_e32 v78, v66
	v_mov_b32_e32 v79, v66
	v_mov_b32_e32 v80, v66
	v_mov_b32_e32 v81, v66
	s_waitcnt lgkmcnt(7)
	s_nop 0
	v_mfma_f32_32x32x16_bf16 v[82:97], v[160:163], v[100:103], v[66:81]
	s_waitcnt lgkmcnt(5)
	v_mfma_f32_32x32x16_bf16 v[66:81], v[168:171], v[100:103], v[66:81]
	v_mfma_f32_32x32x16_bf16 v[82:97], v[164:167], v[104:107], v[82:97]
	s_waitcnt lgkmcnt(4)
	v_mfma_f32_32x32x16_bf16 v[66:81], v[172:175], v[104:107], v[66:81]
	s_waitcnt lgkmcnt(3)
	v_mfma_f32_32x32x16_bf16 v[82:97], v[176:179], v[108:111], v[82:97]
	s_waitcnt lgkmcnt(1)
	v_mfma_f32_32x32x16_bf16 v[66:81], v[192:195], v[108:111], v[66:81]
	v_mfma_f32_32x32x16_bf16 v[82:97], v[180:183], v[112:115], v[82:97]
	s_waitcnt lgkmcnt(0)
	v_mfma_f32_32x32x16_bf16 v[66:81], v[196:199], v[112:115], v[66:81]
	s_add_i32 s14, s12, 0x42
	s_cmp_ge_i32 s14, s6
	s_cbranch_scc1 .Lpipe_nostage_p
	s_mul_i32 s4, s7, 0x8c00
	s_add_i32 s4, s4, 0
	v_add_u32_e32 v184, s4, v140
	v_add_u32_e32 v185, v184, v139
	v_add_u32_e32 v184, v184, v141
	s_waitcnt vmcnt(3)
	ds_write_b128 v185, v[116:119]
	s_waitcnt vmcnt(2)
	ds_write_b128 v184, v[120:123]
	v_add3_u32 v184, s4, v150, v151
	v_add_u32_e32 v185, v184, v152
	v_add_u32_e32 v184, v184, v153
	v_add_u32_e32 v185, 0x4000, v185
	v_add_u32_e32 v184, 0x4000, v184
	s_waitcnt vmcnt(1)
	ds_write2_b64 v185, v[124:125], v[126:127] offset0:128 offset1:130
	s_waitcnt vmcnt(0)
	ds_write2_b64 v184, v[128:129], v[130:131] offset0:128 offset1:130
	s_add_i32 s14, s12, 0x43
	s_cmp_ge_i32 s14, s6
	s_cbranch_scc1 .Lpipe_nostage_p
	v_add_co_u32_e32 v184, vcc, 0x10000, v144
	global_load_dwordx4 v[116:119], v[144:145], off
	s_nop 0
	v_addc_co_u32_e32 v185, vcc, 0, v145, vcc
	global_load_dwordx4 v[120:123], v[184:185], off
	global_load_dwordx4 v[124:127], v[142:143], off
	v_add_co_u32_e32 v184, vcc, 0x80000, v142
	v_lshl_add_u64 v[144:145], v[144:145], 0, s[90:91]
	s_nop 0
	v_addc_co_u32_e32 v185, vcc, 0, v143, vcc
	global_load_dwordx4 v[128:131], v[184:185], off
	v_lshl_add_u64 v[142:143], v[142:143], 0, s[88:89]

; DI void attn_s(const unsigned char* sK, int tt, int qb, int qs, int sub, int l31, int h,
;                const bf16x8 (&qf)[4], f32x16 (&O)[4], float& m, float& l, bf16x8 (&pb)[4]) {
;     ...
;     } else if (tt >= 2 * qb + 1) {
;         const int kbase = (tt - 1) * 64 + 4 * h;
; #pragma unroll
;         for (int k2 = 0; k2 < 2; ++k2)
; #pragma unroll
;             for (int i = 0; i < 16; ++i) {
;                 const int key = kbase + k2 * 32 + (i & 3) + 8 * (i >> 2);
;                 if (key > qs) st[k2][i] = -INFINITY;
;             }
;     }
; DI void attn_pv(const unsigned char* sV, int l31, int h, const bf16x8 (&pb)[4], f32x16 (&O)[4]) {
;     ...
;         const unsigned char* vb = sV + l31 * A_VROWB + 16 * h;
;         bf16x8 va[4], vc[4];
; #pragma unroll
;         for (int d = 0; d < 4; ++d) va[d] = *(const bf16x8*)(vb + d * 32 * A_VROWB);
;         __builtin_amdgcn_sched_barrier(0);
; #pragma unroll
;         for (int d = 0; d < 4; ++d) vc[d] = *(const bf16x8*)(vb + d * 32 * A_VROWB + 32);
.Lpipe_loop:
	v_add3_u32 v191, s98, v156, v98
	ds_read_b128 v[172:175], v191 offset:17408
	ds_read_b128 v[176:179], v191 offset:22016
	ds_read_b128 v[180:183], v191 offset:26624
	ds_read_b128 v[192:195], v191 offset:31232
	ds_read_b128 v[200:203], v191 offset:17440
	ds_read_b128 v[204:207], v191 offset:22048
	ds_read_b128 v[208:211], v191 offset:26656
	ds_read_b128 v[212:215], v191 offset:31264
	s_add_i32 s14, s12, 0x41
	s_cmp_le_i32 s14, s0
	s_cbranch_scc1 .Lpipe_nomask_l
	v_subrev_u32_e32 v159, 59, v158
	v_cmp_gt_i32_e32 vcc, v159, v138
	s_nop 6
	v_cndmask_b32_e32 v160, v82, v188, vcc
	v_cmp_lt_i32_e32 vcc, v159, v138
	v_subrev_u32_e32 v159, 57, v158
	s_nop 0
	v_cndmask_b32_e32 v82, v160, v82, vcc
	v_cndmask_b32_e32 v83, v188, v83, vcc
	v_cmp_le_i32_e32 vcc, v159, v138
	v_subrev_u32_e32 v159, 56, v158
	s_nop 0
	v_cndmask_b32_e32 v84, v188, v84, vcc
	v_cmp_le_i32_e32 vcc, v159, v138
	v_subrev_u32_e32 v159, 51, v158
	s_nop 0
	v_cndmask_b32_e32 v85, v188, v85, vcc
	v_cmp_le_i32_e32 vcc, v159, v138
	v_subrev_u32_e32 v159, 50, v158
	s_nop 0
	v_cndmask_b32_e32 v86, v188, v86, vcc
	v_cmp_le_i32_e32 vcc, v159, v138
	v_subrev_u32_e32 v159, 49, v158
	s_nop 0
	v_cndmask_b32_e32 v87, v188, v87, vcc
	v_cmp_le_i32_e32 vcc, v159, v138
	v_subrev_u32_e32 v159, 48, v158
	s_nop 0
	v_cndmask_b32_e32 v88, v188, v88, vcc
	v_cmp_le_i32_e32 vcc, v159, v138
	v_subrev_u32_e32 v159, 43, v158
	s_nop 0
	v_cndmask_b32_e32 v89, v188, v89, vcc
	v_cmp_le_i32_e32 vcc, v159, v138
	v_subrev_u32_e32 v159, 42, v158
	s_nop 0
	v_cndmask_b32_e32 v90, v188, v90, vcc
	v_cmp_le_i32_e32 vcc, v159, v138
	v_subrev_u32_e32 v159, 41, v158
	s_nop 0
	v_cndmask_b32_e32 v91, v188, v91, vcc
	v_cmp_le_i32_e32 vcc, v159, v138
	v_subrev_u32_e32 v159, 40, v158
	s_nop 0
	v_cndmask_b32_e32 v92, v188, v92, vcc
	v_cmp_le_i32_e32 vcc, v159, v138
	v_subrev_u32_e32 v159, 35, v158
	s_nop 0
	v_cndmask_b32_e32 v93, v188, v93, vcc
	v_cmp_le_i32_e32 vcc, v159, v138
	v_subrev_u32_e32 v159, 34, v158
	s_nop 0
	v_cndmask_b32_e32 v94, v188, v94, vcc
	v_cmp_le_i32_e32 vcc, v159, v138
	v_subrev_u32_e32 v159, 33, v158
	s_nop 0
	v_cndmask_b32_e32 v95, v188, v95, vcc
	v_cmp_le_i32_e32 vcc, v159, v138
	v_subrev_u32_e32 v159, 32, v158
	s_nop 0
	v_cndmask_b32_e32 v96, v188, v96, vcc
	v_cmp_le_i32_e32 vcc, v159, v138
	v_subrev_u32_e32 v159, 27, v158
	s_nop 0
	v_cndmask_b32_e32 v97, v188, v97, vcc
	v_cmp_le_i32_e32 vcc, v159, v138
	v_subrev_u32_e32 v159, 26, v158
	s_nop 0
	v_cndmask_b32_e32 v66, v188, v66, vcc
	v_cmp_le_i32_e32 vcc, v159, v138
	v_subrev_u32_e32 v159, 25, v158
	s_nop 0
	v_cndmask_b32_e32 v67, v188, v67, vcc
	v_cmp_le_i32_e32 vcc, v159, v138
	v_subrev_u32_e32 v159, 24, v158
	s_nop 0
	v_cndmask_b32_e32 v68, v188, v68, vcc
	v_cmp_le_i32_e32 vcc, v159, v138
	v_subrev_u32_e32 v159, 19, v158
	s_nop 0
	v_cndmask_b32_e32 v69, v188, v69, vcc
	v_cmp_le_i32_e32 vcc, v159, v138
	v_subrev_u32_e32 v159, 18, v158
	s_nop 0
	v_cndmask_b32_e32 v70, v188, v70, vcc
	v_cmp_le_i32_e32 vcc, v159, v138
	v_subrev_u32_e32 v159, 17, v158
	s_nop 0
	v_cndmask_b32_e32 v71, v188, v71, vcc
	v_cmp_le_i32_e32 vcc, v159, v138
	v_add_u32_e32 v159, -16, v158
	s_nop 0
	v_cndmask_b32_e32 v72, v188, v72, vcc
	v_cmp_le_i32_e32 vcc, v159, v138
	v_add_u32_e32 v159, -11, v158
	s_nop 0
	v_cndmask_b32_e32 v73, v188, v73, vcc
	v_cmp_le_i32_e32 vcc, v159, v138
	v_add_u32_e32 v159, -10, v158
	s_nop 0
	v_cndmask_b32_e32 v74, v188, v74, vcc
	v_cmp_le_i32_e32 vcc, v159, v138
	v_add_u32_e32 v159, -9, v158
	s_nop 0
	v_cndmask_b32_e32 v75, v188, v75, vcc
	v_cmp_le_i32_e32 vcc, v159, v138
	v_add_u32_e32 v159, -8, v158
	s_nop 0
	v_cndmask_b32_e32 v76, v188, v76, vcc
	v_cmp_le_i32_e32 vcc, v159, v138
	v_add_u32_e32 v159, -3, v158
	s_nop 0
	v_cndmask_b32_e32 v77, v188, v77, vcc
	v_cmp_le_i32_e32 vcc, v159, v138
	v_add_u32_e32 v159, -2, v158
	s_nop 0
	v_cndmask_b32_e32 v78, v188, v78, vcc
	v_cmp_le_i32_e32 vcc, v159, v138
	v_add_u32_e32 v159, -1, v158
	s_nop 0
	v_cndmask_b32_e32 v79, v188, v79, vcc
	v_cmp_le_i32_e32 vcc, v159, v138
	s_nop 1
	v_cndmask_b32_e32 v80, v188, v80, vcc
	v_cmp_le_i32_e32 vcc, v158, v138
	s_nop 1
	v_cndmask_b32_e32 v81, v188, v81, vcc

; #define MFMA32(a, b, c) __builtin_amdgcn_mfma_f32_32x32x16_bf16((a), (b), (c), 0, 0, 0)
; DI void attn_s(const unsigned char* sK, int tt, int qb, int qs, int sub, int l31, int h,
;                const bf16x8 (&qf)[4], f32x16 (&O)[4], float& m, float& l, bf16x8 (&pb)[4]) {
;     ...
; #pragma unroll
;     for (int k2 = 0; k2 < 2; ++k2)
; #pragma unroll
;         for (int i = 0; i < 16; ++i) st[k2][i] = __builtin_amdgcn_exp2f(st[k2][i]);
;     {
;         const f32x16 sv = st[0] + st[1];
;         const float ps = (((sv[0] + sv[1]) + (sv[2] + sv[3])) + ((sv[4] + sv[5]) + (sv[6] + sv[7]))) + (((sv[8] + sv[9]) + (sv[10] + sv[11])) + ((sv[12] + sv[13]) + (sv[14] + sv[15])));
;         l += ps;
;     }
; #pragma unroll
;     for (int k4 = 0; k4 < 4; ++k4) {
;         const int k2 = k4 >> 1, o8 = 8 * (k4 & 1);
;         u32x4 pk;
;         pk.x = pk2(st[k2][o8 + 0], st[k2][o8 + 1]); pk.y = pk2(st[k2][o8 + 2], st[k2][o8 + 3]);
;         pk.z = pk2(st[k2][o8 + 4], st[k2][o8 + 5]); pk.w = pk2(st[k2][o8 + 6], st[k2][o8 + 7]);
;         pb[k4] = __builtin_bit_cast(bf16x8, pk);
;     }
; DI void attn_pv(const unsigned char* sV, int l31, int h, const bf16x8 (&pb)[4], f32x16 (&O)[4]) {
;     ...
;         for (int d = 0; d < 4; ++d) va[d] = *(const bf16x8*)(vb + d * 32 * A_VROWB);
;         __builtin_amdgcn_sched_barrier(0);
; #pragma unroll
;         for (int d = 0; d < 4; ++d) vc[d] = *(const bf16x8*)(vb + d * 32 * A_VROWB + 32);
;         __builtin_amdgcn_sched_barrier(0);
; #pragma unroll
;         for (int d = 0; d < 4; ++d) O[d] = MFMA32(va[d], pb[0], O[d]);
;         __builtin_amdgcn_sched_barrier(0);
; #pragma unroll
;         for (int d = 0; d < 4; ++d) va[d] = *(const bf16x8*)(vb + d * 32 * A_VROWB + 64);
;         __builtin_amdgcn_sched_barrier(0);
; #pragma unroll
;         for (int d = 0; d < 4; ++d) O[d] = MFMA32(vc[d], pb[1], O[d]);
;         __builtin_amdgcn_sched_barrier(0);
; #pragma unroll
;         for (int d = 0; d < 4; ++d) vc[d] = *(const bf16x8*)(vb + d * 32 * A_VROWB + 96);
;         __builtin_amdgcn_sched_barrier(0);
; #pragma unroll
;         for (int d = 0; d < 4; ++d) O[d] = MFMA32(va[d], pb[2], O[d]);
;         __builtin_amdgcn_sched_barrier(0);
; #pragma unroll
;         for (int d = 0; d < 4; ++d) O[d] = MFMA32(vc[d], pb[3], O[d]);
.Lpipe_norescale_l:
	v_exp_f32_e32 v82, v82
	v_exp_f32_e32 v83, v83
	v_exp_f32_e32 v84, v84
	v_exp_f32_e32 v85, v85
	v_exp_f32_e32 v86, v86
	v_exp_f32_e32 v87, v87
	v_exp_f32_e32 v88, v88
	v_exp_f32_e32 v89, v89
	v_exp_f32_e32 v90, v90
	v_exp_f32_e32 v91, v91
	v_exp_f32_e32 v92, v92
	v_exp_f32_e32 v93, v93
	v_exp_f32_e32 v94, v94
	v_exp_f32_e32 v95, v95
	v_exp_f32_e32 v96, v96
	v_exp_f32_e32 v97, v97
	v_exp_f32_e32 v66, v66
	v_exp_f32_e32 v67, v67
	v_exp_f32_e32 v68, v68
	v_exp_f32_e32 v69, v69
	v_exp_f32_e32 v70, v70
	v_exp_f32_e32 v71, v71
	v_exp_f32_e32 v72, v72
	v_exp_f32_e32 v73, v73
	v_exp_f32_e32 v74, v74
	v_exp_f32_e32 v75, v75
	v_exp_f32_e32 v76, v76
	v_exp_f32_e32 v77, v77
	v_exp_f32_e32 v78, v78
	v_exp_f32_e32 v79, v79
	v_exp_f32_e32 v80, v80
	v_exp_f32_e32 v81, v81
	v_cvt_pk_bf16_f32 v216, v82, v83
	v_cvt_pk_bf16_f32 v217, v84, v85
	v_cvt_pk_bf16_f32 v218, v86, v87
	v_cvt_pk_bf16_f32 v219, v88, v89
	v_cvt_pk_bf16_f32 v220, v90, v91
	v_cvt_pk_bf16_f32 v221, v92, v93
	v_cvt_pk_bf16_f32 v222, v94, v95
	v_cvt_pk_bf16_f32 v223, v96, v97
	v_cvt_pk_bf16_f32 v224, v66, v67
	v_cvt_pk_bf16_f32 v225, v68, v69
	v_cvt_pk_bf16_f32 v226, v70, v71
	v_cvt_pk_bf16_f32 v227, v72, v73
	v_cvt_pk_bf16_f32 v228, v74, v75
	v_cvt_pk_bf16_f32 v229, v76, v77
	v_cvt_pk_bf16_f32 v230, v78, v79
	v_cvt_pk_bf16_f32 v231, v80, v81
	v_pk_add_f32 v[68:69], v[84:85], v[68:69]
	v_pk_add_f32 v[66:67], v[82:83], v[66:67]
	v_pk_add_f32 v[72:73], v[88:89], v[72:73]
	v_pk_add_f32 v[70:71], v[86:87], v[70:71]
	v_add_f32_e32 v66, v66, v67
	v_add_f32_e32 v67, v68, v69
	v_add_f32_e32 v66, v66, v67
	v_add_f32_e32 v67, v70, v71
	v_add_f32_e32 v68, v72, v73
	v_pk_add_f32 v[76:77], v[92:93], v[76:77]
	v_pk_add_f32 v[74:75], v[90:91], v[74:75]
	v_add_f32_e32 v67, v67, v68
	v_pk_add_f32 v[80:81], v[96:97], v[80:81]
	v_pk_add_f32 v[78:79], v[94:95], v[78:79]
	v_add_f32_e32 v66, v66, v67
	v_add_f32_e32 v67, v74, v75
	v_add_f32_e32 v68, v76, v77
	v_add_f32_e32 v67, v67, v68
	v_add_f32_e32 v68, v78, v79
	v_add_f32_e32 v69, v80, v81
	v_add_f32_e32 v68, v68, v69
	v_add_f32_e32 v67, v67, v68
	v_add_f32_e32 v66, v66, v67
	v_add_f32_e32 v1, v1, v66
	v_add_u32_e32 v158, 64, v158
	s_mov_b32 s13, s7
	s_add_i32 s4, s7, 1
	s_cmp_lg_u32 s7, 2
	s_cselect_b32 s7, s4, 0
	s_add_i32 s12, s12, 1
	s_cmp_eq_u32 s11, s12
	s_cbranch_scc1 .Lpipe_final
	s_barrier
	s_mul_i32 s98, s13, 0x8c00
	v_add3_u32 v185, s98, v155, v154
	ds_read_b128 v[160:163], v185
	ds_read_b128 v[164:167], v185 offset:32
	ds_read_b128 v[168:171], v185 offset:8704
	ds_read_b128 v[196:199], v185 offset:8736
	s_waitcnt lgkmcnt(11)
	v_mfma_f32_32x32x16_bf16 v[50:65], v[172:175], v[216:219], v[50:65]
	s_waitcnt lgkmcnt(10)
	v_mfma_f32_32x32x16_bf16 v[34:49], v[176:179], v[216:219], v[34:49]
	s_waitcnt lgkmcnt(9)
	v_mfma_f32_32x32x16_bf16 v[18:33], v[180:183], v[216:219], v[18:33]
	s_waitcnt lgkmcnt(8)
	v_mfma_f32_32x32x16_bf16 v[2:17], v[192:195], v[216:219], v[2:17]
	ds_read_b128 v[172:175], v185 offset:64
	ds_read_b128 v[176:179], v185 offset:96
	ds_read_b128 v[180:183], v185 offset:8768
	ds_read_b128 v[192:195], v185 offset:8800
	v_xor_b32_e32 v66, 0x80000000, v157
	v_mov_b32_e32 v67, v66
	v_mov_b32_e32 v68, v66
	v_mov_b32_e32 v69, v66
	v_mov_b32_e32 v70, v66
	v_mov_b32_e32 v71, v66
	v_mov_b32_e32 v72, v66
	v_mov_b32_e32 v73, v66
	v_mov_b32_e32 v74, v66
	v_mov_b32_e32 v75, v66
	v_mov_b32_e32 v76, v66
	v_mov_b32_e32 v77, v66
	v_mov_b32_e32 v78, v66
	v_mov_b32_e32 v79, v66
	v_mov_b32_e32 v80, v66
	v_mov_b32_e32 v81, v66
	s_waitcnt lgkmcnt(11)
	v_mfma_f32_32x32x16_bf16 v[50:65], v[200:203], v[220:223], v[50:65]
	s_waitcnt lgkmcnt(10)
	v_mfma_f32_32x32x16_bf16 v[34:49], v[204:207], v[220:223], v[34:49]
	s_waitcnt lgkmcnt(9)
	v_mfma_f32_32x32x16_bf16 v[18:33], v[208:211], v[220:223], v[18:33]
	s_waitcnt lgkmcnt(8)
	v_mfma_f32_32x32x16_bf16 v[2:17], v[212:215], v[220:223], v[2:17]
	ds_read_b128 v[200:203], v191 offset:17472
	ds_read_b128 v[204:207], v191 offset:22080
	ds_read_b128 v[208:211], v191 offset:26688
	ds_read_b128 v[212:215], v191 offset:31296
	s_waitcnt lgkmcnt(11)
	v_mfma_f32_32x32x16_bf16 v[82:97], v[160:163], v[100:103], v[66:81]
	s_waitcnt lgkmcnt(9)
	v_mfma_f32_32x32x16_bf16 v[66:81], v[168:171], v[100:103], v[66:81]
	v_mfma_f32_32x32x16_bf16 v[82:97], v[164:167], v[104:107], v[82:97]
	s_waitcnt lgkmcnt(8)
	v_mfma_f32_32x32x16_bf16 v[66:81], v[196:199], v[104:107], v[66:81]
	ds_read_b128 v[160:163], v191 offset:17504
	ds_read_b128 v[164:167], v191 offset:22112
	ds_read_b128 v[168:171], v191 offset:26720
	ds_read_b128 v[196:199], v191 offset:31328
	s_waitcnt lgkmcnt(11)
	v_mfma_f32_32x32x16_bf16 v[82:97], v[172:175], v[108:111], v[82:97]
	s_waitcnt lgkmcnt(9)
	v_mfma_f32_32x32x16_bf16 v[66:81], v[180:183], v[108:111], v[66:81]
	v_mfma_f32_32x32x16_bf16 v[82:97], v[176:179], v[112:115], v[82:97]
	s_waitcnt lgkmcnt(8)
	v_mfma_f32_32x32x16_bf16 v[66:81], v[192:195], v[112:115], v[66:81]
	s_add_i32 s14, s12, 0x42
	s_cmp_ge_i32 s14, s6
	s_cbranch_scc1 .Lpipe_nost_l
	s_mul_i32 s4, s7, 0x8c00
	s_add_i32 s4, s4, 0
	v_add_u32_e32 v184, s4, v140
	v_add_u32_e32 v185, v184, v139
	v_add_u32_e32 v184, v184, v141
	s_waitcnt vmcnt(3)
	ds_write_b128 v185, v[116:119]
	s_waitcnt vmcnt(2)
	ds_write_b128 v184, v[120:123]
	v_add3_u32 v184, s4, v150, v151
	v_add_u32_e32 v185, v184, v152
	v_add_u32_e32 v184, v184, v153
	v_add_u32_e32 v185, 0x4000, v185
	v_add_u32_e32 v184, 0x4000, v184
	s_waitcnt vmcnt(1)
	ds_write2_b64 v185, v[124:125], v[126:127] offset0:128 offset1:130
	s_waitcnt vmcnt(0)
	ds_write2_b64 v184, v[128:129], v[130:131] offset0:128 offset1:130
.Lpipe_nost_l:
	s_waitcnt lgkmcnt(7)
	v_mfma_f32_32x32x16_bf16 v[50:65], v[200:203], v[224:227], v[50:65]
	s_waitcnt lgkmcnt(6)
	v_mfma_f32_32x32x16_bf16 v[34:49], v[204:207], v[224:227], v[34:49]
	s_waitcnt lgkmcnt(5)
	v_mfma_f32_32x32x16_bf16 v[18:33], v[208:211], v[224:227], v[18:33]
	s_waitcnt lgkmcnt(4)
	v_mfma_f32_32x32x16_bf16 v[2:17], v[212:215], v[224:227], v[2:17]
	s_waitcnt lgkmcnt(3)
	v_mfma_f32_32x32x16_bf16 v[50:65], v[160:163], v[228:231], v[50:65]
	s_waitcnt lgkmcnt(2)
	v_mfma_f32_32x32x16_bf16 v[34:49], v[164:167], v[228:231], v[34:49]
	s_waitcnt lgkmcnt(1)
	v_mfma_f32_32x32x16_bf16 v[18:33], v[168:171], v[228:231], v[18:33]
	s_waitcnt lgkmcnt(0)
	v_mfma_f32_32x32x16_bf16 v[2:17], v[196:199], v[228:231], v[2:17]
	s_add_i32 s14, s12, 0x43
	s_cmp_ge_i32 s14, s6
	s_cbranch_scc1 .Lpipe_nopf_l
	v_add_co_u32_e32 v184, vcc, 0x10000, v144
	global_load_dwordx4 v[116:119], v[144:145], off
	s_nop 0
	v_addc_co_u32_e32 v185, vcc, 0, v145, vcc
	global_load_dwordx4 v[120:123], v[184:185], off
	global_load_dwordx4 v[124:127], v[142:143], off
	v_add_co_u32_e32 v184, vcc, 0x80000, v142
	v_lshl_add_u64 v[144:145], v[144:145], 0, s[90:91]
	s_nop 0
	v_addc_co_u32_e32 v185, vcc, 0, v143, vcc
	global_load_dwordx4 v[128:131], v[184:185], off
	v_lshl_add_u64 v[142:143], v[142:143], 0, s[88:89]
